# GEMM epilogues of w_in (bf16 paths) and MLP1 regrouped through LDS: each store covers 4 rows x 256 contiguous bytes
# speedup vs baseline: 1.0065x; 1.0065x over previous
; __device__ __forceinline__ unsigned pk2(float lo, float hi) { const v2f_t f = {lo, hi}; const v2bf_t b = __builtin_convertvector(f, v2bf_t); return __builtin_bit_cast(unsigned, b); }
;     __device__ __forceinline__ void operator()(const f32x4 (&acc)[2][2][4][2], const Unit& u, int wr, int wc, int fr, int fq) const {
;     ...
;         } else if (u.pn < 16) {
;             bf16_t* base; int ld, colt;
;             if (u.pn < 2) { base = pk; ld = 512; colt = u.pn * 256; }
;             else if (u.pn < 8) { base = pq; ld = 512; colt = (u.pn - 6) * 256; }
;             else if (u.pn < 12) { base = pg; ld = 1024; colt = (u.pn - 8) * 256; }
;             else { base = pu; ld = 1024; colt = (u.pn - 12) * 256; }
;             const int col0 = colt + wc * 32 + 8 * fq;
; #pragma unroll
;             for (int ai = 0; ai < 2; ++ai)
; #pragma unroll
;                 for (int m = 0; m < 4; ++m) { bf16_t* rowp = base + (size_t)(row0 + ai * 128 + m * 16) * ld + col0;
; #pragma unroll
;                     for (int bj = 0; bj < 2; ++bj) { const f32x4 v0 = acc[ai][bj][m][0], v1 = acc[ai][bj][m][1];
;                         u32x4 w; w.x = pk2(v0[0], v0[1]); w.y = pk2(v0[2], v0[3]); w.z = pk2(v1[0], v1[1]); w.w = pk2(v1[2], v1[3]);
;                         *(u32x4*)(rowp + bj * 128) = w; } }
.LBB0_255:
	v_and_b32_e32 v157, 15, v194
	v_bfe_u32 v158, v194, 6, 2
	v_bfe_u32 v159, v194, 4, 2
	v_bfe_u32 v156, v194, 8, 1
	v_lshlrev_b32_e32 v156, 4, v156
	v_add_u32_e32 v156, v156, v157
	v_mul_u32_u24_e32 v186, 0x110, v156
	v_lshl_add_u32 v186, v158, 6, v186
	v_lshl_add_u32 v186, v159, 4, v186
	v_add_u32_e32 v186, 0x23410, v186
	v_lshrrev_b32_e32 v160, 6, v194
	v_lshl_add_u32 v160, v160, 2, v159
	v_mul_u32_u24_e32 v187, 0x110, v160
	v_lshl_add_u32 v187, v157, 4, v187
	v_add_u32_e32 v187, 0x23410, v187
	v_sub_u32_e32 v156, v142, v157
	v_lshl_add_u32 v156, v158, 2, v156
	v_add_u32_e32 v156, v156, v159
	v_mul_lo_u32 v156, v156, s48
	v_lshlrev_b32_e32 v156, 1, v156
	v_lshlrev_b32_e32 v160, 4, v157
	v_lshl_add_u32 v160, s39, 1, v160
	v_add_u32_e32 v156, v156, v160
	v_mov_b32_e32 v157, 0
	v_lshl_add_u64 v[188:189], s[50:51], 0, v[156:157]
	s_mov_b32 s99, 0
	s_mul_i32 s98, s48, 0
	v_lshl_add_u64 v[190:191], v[188:189], 0, s[98:99]
	v_cvt_pk_bf16_f32 v174, v126, v127
	v_cvt_pk_bf16_f32 v175, v128, v129
	v_cvt_pk_bf16_f32 v176, v122, v123
	v_cvt_pk_bf16_f32 v177, v124, v125
	ds_write_b128 v186, v[174:177]
	s_waitcnt lgkmcnt(0)
	s_barrier
	ds_read_b128 v[178:181], v187
	s_waitcnt lgkmcnt(0)
	global_store_dwordx4 v[190:191], v[178:181], off
	v_cvt_pk_bf16_f32 v174, v118, v119
	v_cvt_pk_bf16_f32 v175, v120, v121
	v_cvt_pk_bf16_f32 v176, v114, v115
	v_cvt_pk_bf16_f32 v177, v116, v117
	ds_write_b128 v186, v[174:177] offset:8704
	s_waitcnt lgkmcnt(0)
	s_barrier
	ds_read_b128 v[182:185], v187 offset:8704
	s_waitcnt lgkmcnt(0)
	global_store_dwordx4 v[190:191], v[182:185], off offset:256
	s_mul_i32 s98, s48, 32
	v_lshl_add_u64 v[190:191], v[188:189], 0, s[98:99]
	v_cvt_pk_bf16_f32 v174, v110, v111
	v_cvt_pk_bf16_f32 v175, v112, v113
	v_cvt_pk_bf16_f32 v176, v106, v107
	v_cvt_pk_bf16_f32 v177, v108, v109
	ds_write_b128 v186, v[174:177]
	s_waitcnt lgkmcnt(0)
	s_barrier
	ds_read_b128 v[178:181], v187
	s_waitcnt lgkmcnt(0)
	global_store_dwordx4 v[190:191], v[178:181], off
	v_cvt_pk_bf16_f32 v174, v102, v103
	v_cvt_pk_bf16_f32 v175, v104, v105
	v_cvt_pk_bf16_f32 v176, v98, v99
	v_cvt_pk_bf16_f32 v177, v100, v101
	ds_write_b128 v186, v[174:177] offset:8704
	s_waitcnt lgkmcnt(0)
	s_barrier
	ds_read_b128 v[182:185], v187 offset:8704
	s_waitcnt lgkmcnt(0)
	global_store_dwordx4 v[190:191], v[182:185], off offset:256
	s_mul_i32 s98, s48, 64
	v_lshl_add_u64 v[190:191], v[188:189], 0, s[98:99]
	v_cvt_pk_bf16_f32 v174, v94, v95
	v_cvt_pk_bf16_f32 v175, v96, v97
	v_cvt_pk_bf16_f32 v176, v90, v91
	v_cvt_pk_bf16_f32 v177, v92, v93
	ds_write_b128 v186, v[174:177]
	s_waitcnt lgkmcnt(0)
	s_barrier
	ds_read_b128 v[178:181], v187
	s_waitcnt lgkmcnt(0)
	global_store_dwordx4 v[190:191], v[178:181], off
	v_cvt_pk_bf16_f32 v174, v86, v87
	v_cvt_pk_bf16_f32 v175, v88, v89
	v_cvt_pk_bf16_f32 v176, v82, v83
	v_cvt_pk_bf16_f32 v177, v84, v85
	ds_write_b128 v186, v[174:177] offset:8704
	s_waitcnt lgkmcnt(0)
	s_barrier
	ds_read_b128 v[182:185], v187 offset:8704
	s_waitcnt lgkmcnt(0)
	global_store_dwordx4 v[190:191], v[182:185], off offset:256
	s_mul_i32 s98, s48, 96
	v_lshl_add_u64 v[190:191], v[188:189], 0, s[98:99]
	v_cvt_pk_bf16_f32 v174, v78, v79
	v_cvt_pk_bf16_f32 v175, v80, v81
	v_cvt_pk_bf16_f32 v176, v74, v75
	v_cvt_pk_bf16_f32 v177, v76, v77
	ds_write_b128 v186, v[174:177]
	s_waitcnt lgkmcnt(0)
	s_barrier
	ds_read_b128 v[178:181], v187
	s_waitcnt lgkmcnt(0)
	global_store_dwordx4 v[190:191], v[178:181], off
	v_cvt_pk_bf16_f32 v174, v70, v71
	v_cvt_pk_bf16_f32 v175, v72, v73
	v_cvt_pk_bf16_f32 v176, v66, v67
	v_cvt_pk_bf16_f32 v177, v68, v69
	ds_write_b128 v186, v[174:177] offset:8704
	s_waitcnt lgkmcnt(0)
	s_barrier
	ds_read_b128 v[182:185], v187 offset:8704
	s_waitcnt lgkmcnt(0)
	global_store_dwordx4 v[190:191], v[182:185], off offset:256
	s_mul_i32 s98, s48, 256
	v_lshl_add_u64 v[190:191], v[188:189], 0, s[98:99]
	v_cvt_pk_bf16_f32 v174, v60, v61
	v_cvt_pk_bf16_f32 v175, v62, v63
	v_cvt_pk_bf16_f32 v176, v56, v57
	v_cvt_pk_bf16_f32 v177, v58, v59
	ds_write_b128 v186, v[174:177]
	s_waitcnt lgkmcnt(0)
	s_barrier
	ds_read_b128 v[178:181], v187
	s_waitcnt lgkmcnt(0)
	global_store_dwordx4 v[190:191], v[178:181], off
	v_cvt_pk_bf16_f32 v174, v52, v53
	v_cvt_pk_bf16_f32 v175, v54, v55
	v_cvt_pk_bf16_f32 v176, v48, v49
	v_cvt_pk_bf16_f32 v177, v50, v51
	ds_write_b128 v186, v[174:177] offset:8704
	s_waitcnt lgkmcnt(0)
	s_barrier
	ds_read_b128 v[182:185], v187 offset:8704
	s_waitcnt lgkmcnt(0)
	global_store_dwordx4 v[190:191], v[182:185], off offset:256
	s_mul_i32 s98, s48, 288
	v_lshl_add_u64 v[190:191], v[188:189], 0, s[98:99]
	v_cvt_pk_bf16_f32 v174, v44, v45
	v_cvt_pk_bf16_f32 v175, v46, v47
	v_cvt_pk_bf16_f32 v176, v40, v41
	v_cvt_pk_bf16_f32 v177, v42, v43
	ds_write_b128 v186, v[174:177]
	s_waitcnt lgkmcnt(0)
	s_barrier
	ds_read_b128 v[178:181], v187
	s_waitcnt lgkmcnt(0)
	global_store_dwordx4 v[190:191], v[178:181], off
	v_cvt_pk_bf16_f32 v174, v36, v37
	v_cvt_pk_bf16_f32 v175, v38, v39
	v_cvt_pk_bf16_f32 v176, v32, v33
	v_cvt_pk_bf16_f32 v177, v34, v35
	ds_write_b128 v186, v[174:177] offset:8704
	s_waitcnt lgkmcnt(0)
	s_barrier
	ds_read_b128 v[182:185], v187 offset:8704
	s_waitcnt lgkmcnt(0)
	global_store_dwordx4 v[190:191], v[182:185], off offset:256
	s_mul_i32 s98, s48, 320
	v_lshl_add_u64 v[190:191], v[188:189], 0, s[98:99]
	v_cvt_pk_bf16_f32 v174, v28, v29
	v_cvt_pk_bf16_f32 v175, v30, v31
	v_cvt_pk_bf16_f32 v176, v24, v25
	v_cvt_pk_bf16_f32 v177, v26, v27
	ds_write_b128 v186, v[174:177]
	s_waitcnt lgkmcnt(0)
	s_barrier
	ds_read_b128 v[178:181], v187
	s_waitcnt lgkmcnt(0)
	global_store_dwordx4 v[190:191], v[178:181], off
	v_cvt_pk_bf16_f32 v174, v20, v21
	v_cvt_pk_bf16_f32 v175, v22, v23
	v_cvt_pk_bf16_f32 v176, v16, v17
	v_cvt_pk_bf16_f32 v177, v18, v19
	ds_write_b128 v186, v[174:177] offset:8704
	s_waitcnt lgkmcnt(0)
	s_barrier
	ds_read_b128 v[182:185], v187 offset:8704
	s_waitcnt lgkmcnt(0)
	global_store_dwordx4 v[190:191], v[182:185], off offset:256
	s_mul_i32 s98, s48, 352
	v_lshl_add_u64 v[190:191], v[188:189], 0, s[98:99]
	v_cvt_pk_bf16_f32 v174, v12, v13
	v_cvt_pk_bf16_f32 v175, v14, v15
	v_cvt_pk_bf16_f32 v176, v8, v9
	v_cvt_pk_bf16_f32 v177, v10, v11
	ds_write_b128 v186, v[174:177]
	s_waitcnt lgkmcnt(0)
	s_barrier
	ds_read_b128 v[178:181], v187
	s_waitcnt lgkmcnt(0)
	global_store_dwordx4 v[190:191], v[178:181], off
	v_cvt_pk_bf16_f32 v174, v4, v5
	v_cvt_pk_bf16_f32 v175, v6, v7
	v_cvt_pk_bf16_f32 v176, v0, v1
	v_cvt_pk_bf16_f32 v177, v2, v3
	ds_write_b128 v186, v[174:177] offset:8704
	s_waitcnt lgkmcnt(0)
	s_barrier
	ds_read_b128 v[182:185], v187 offset:8704
	s_waitcnt lgkmcnt(0)
	global_store_dwordx4 v[190:191], v[182:185], off offset:256

; __device__ __forceinline__ unsigned pk2(float lo, float hi) { const v2f_t f = {lo, hi}; const v2bf_t b = __builtin_convertvector(f, v2bf_t); return __builtin_bit_cast(unsigned, b); }
;     __device__ __forceinline__ void operator()(const f32x4 (&acc)[2][2][4][2], const Unit& u, int wr, int wc, int fr, int fq) const {
;         const int row0 = u.pm * 256 + wr * 64 + fr, col0 = u.pn * 256 + wc * 32 + 8 * fq;
;         f32x4 bv[2][2];
; #pragma unroll
;         for (int bj = 0; bj < 2; ++bj)
; #pragma unroll
;             for (int n = 0; n < 2; ++n) bv[bj][n] = *(const f32x4*)(bias + col0 + bj * 128 + 4 * n);
; #pragma unroll
;         for (int ai = 0; ai < 2; ++ai)
; #pragma unroll
;             for (int m = 0; m < 4; ++m) { bf16_t* rowp = a1 + (size_t)(row0 + ai * 128 + m * 16) * DFF + col0;
; #pragma unroll
;                 for (int bj = 0; bj < 2; ++bj) { f32x4 v0 = acc[ai][bj][m][0] + bv[bj][0], v1 = acc[ai][bj][m][1] + bv[bj][1];
; #pragma unroll
;                     for (int j = 0; j < 4; ++j) { const float a = fmaxf(v0[j], 0.f), b = fmaxf(v1[j], 0.f); v0[j] = a * a; v1[j] = b * b; }
;                     u32x4 w; w.x = pk2(v0[0], v0[1]); w.y = pk2(v0[2], v0[3]); w.z = pk2(v1[0], v1[1]); w.w = pk2(v1[2], v1[3]);
;                     *(u32x4*)(rowp + bj * 128) = w; } }
.LBB0_851:
	v_lshl_or_b32 v156, s34, 8, v172
	v_ashrrev_i32_e32 v157, 31, v156
	v_lshl_add_u64 v[118:119], v[156:157], 2, s[18:19]
	global_load_dwordx4 v[122:125], v[118:119], off offset:16
	global_load_dwordx4 v[126:129], v[118:119], off
	global_load_dwordx4 v[114:117], v[118:119], off offset:528
	s_nop 0
	global_load_dwordx4 v[118:121], v[118:119], off offset:512
	v_bfe_u32 v156, v194, 8, 1
	v_lshlrev_b32_e32 v156, 4, v156
	v_and_b32_e32 v157, 15, v194
	v_add_u32_e32 v156, v156, v157
	v_mul_u32_u24_e32 v186, 0x110, v156
	v_bfe_u32 v158, v194, 6, 2
	v_bfe_u32 v159, v194, 4, 2
	v_lshl_add_u32 v186, v158, 6, v186
	v_lshl_add_u32 v186, v159, 4, v186
	v_add_u32_e32 v186, 0x23410, v186
	v_lshrrev_b32_e32 v160, 6, v194
	v_lshl_add_u32 v160, v160, 2, v159
	v_mul_u32_u24_e32 v187, 0x110, v160
	v_lshl_add_u32 v187, v157, 4, v187
	v_add_u32_e32 v187, 0x23410, v187
	v_bfe_u32 v156, v194, 8, 1
	v_lshlrev_b32_e32 v156, 6, v156
	v_lshl_add_u32 v156, v158, 2, v156
	v_add_u32_e32 v156, v156, v159
	v_lshl_add_u32 v160, s30, 8, v156
	v_mov_b32_e32 v161, 0
	v_lshlrev_b64 v[160:161], 14, v[160:161]
	v_lshlrev_b32_e32 v158, 4, v157
	v_lshl_add_u32 v158, s34, 9, v158
	v_mov_b32_e32 v159, 0
	v_lshl_add_u64 v[188:189], s[14:15], 0, v[160:161]
	v_lshl_add_u64 v[188:189], v[188:189], 0, v[158:159]
	s_mov_b32 s21, 0x200000
	s_mov_b64 s[36:37], 0x200000
	s_mov_b32 s62, s61
	s_mov_b32 s34, s20
	s_mov_b32 s30, s22
	s_mov_b64 s[38:39], s[28:29]
	s_mov_b32 s99, 0
	s_waitcnt vmcnt(0)
	s_mov_b32 s98, 0x0
	v_lshl_add_u64 v[190:191], v[188:189], 0, s[98:99]
	v_pk_add_f32 v[142:143], v[142:143], v[126:127]
	v_pk_add_f32 v[144:145], v[144:145], v[128:129]
	v_max_f32_e32 v142, 0, v142
	v_max_f32_e32 v143, 0, v143
	v_max_f32_e32 v144, 0, v144
	v_max_f32_e32 v145, 0, v145
	v_pk_mul_f32 v[142:143], v[142:143], v[142:143]
	v_pk_mul_f32 v[144:145], v[144:145], v[144:145]
	v_pk_add_f32 v[138:139], v[138:139], v[122:123]
	v_pk_add_f32 v[140:141], v[140:141], v[124:125]
	v_max_f32_e32 v138, 0, v138
	v_max_f32_e32 v139, 0, v139
	v_max_f32_e32 v140, 0, v140
	v_max_f32_e32 v141, 0, v141
	v_pk_mul_f32 v[138:139], v[138:139], v[138:139]
	v_pk_mul_f32 v[140:141], v[140:141], v[140:141]
	v_cvt_pk_bf16_f32 v174, v142, v143
	v_cvt_pk_bf16_f32 v175, v144, v145
	v_cvt_pk_bf16_f32 v176, v138, v139
	v_cvt_pk_bf16_f32 v177, v140, v141
	ds_write_b128 v186, v[174:177]
	s_waitcnt lgkmcnt(0)
	s_barrier
	ds_read_b128 v[178:181], v187
	s_waitcnt lgkmcnt(0)
	global_store_dwordx4 v[190:191], v[178:181], off
	v_pk_add_f32 v[134:135], v[134:135], v[118:119]
	v_pk_add_f32 v[136:137], v[136:137], v[120:121]
	v_max_f32_e32 v134, 0, v134
	v_max_f32_e32 v135, 0, v135
	v_max_f32_e32 v136, 0, v136
	v_max_f32_e32 v137, 0, v137
	v_pk_mul_f32 v[134:135], v[134:135], v[134:135]
	v_pk_mul_f32 v[136:137], v[136:137], v[136:137]
	v_pk_add_f32 v[130:131], v[130:131], v[114:115]
	v_pk_add_f32 v[132:133], v[132:133], v[116:117]
	v_max_f32_e32 v130, 0, v130
	v_max_f32_e32 v131, 0, v131
	v_max_f32_e32 v132, 0, v132
	v_max_f32_e32 v133, 0, v133
	v_pk_mul_f32 v[130:131], v[130:131], v[130:131]
	v_pk_mul_f32 v[132:133], v[132:133], v[132:133]
	v_cvt_pk_bf16_f32 v174, v134, v135
	v_cvt_pk_bf16_f32 v175, v136, v137
	v_cvt_pk_bf16_f32 v176, v130, v131
	v_cvt_pk_bf16_f32 v177, v132, v133
	ds_write_b128 v186, v[174:177] offset:8704
	s_waitcnt lgkmcnt(0)
	s_barrier
	ds_read_b128 v[182:185], v187 offset:8704
	s_waitcnt lgkmcnt(0)
	global_store_dwordx4 v[190:191], v[182:185], off offset:256
	s_mov_b32 s98, 0x40000
	v_lshl_add_u64 v[190:191], v[188:189], 0, s[98:99]
	v_pk_add_f32 v[110:111], v[110:111], v[126:127]
	v_pk_add_f32 v[112:113], v[112:113], v[128:129]
	v_max_f32_e32 v110, 0, v110
	v_max_f32_e32 v111, 0, v111
	v_max_f32_e32 v112, 0, v112
	v_max_f32_e32 v113, 0, v113
	v_pk_mul_f32 v[110:111], v[110:111], v[110:111]
	v_pk_mul_f32 v[112:113], v[112:113], v[112:113]
	v_pk_add_f32 v[106:107], v[106:107], v[122:123]
	v_pk_add_f32 v[108:109], v[108:109], v[124:125]
	v_max_f32_e32 v106, 0, v106
	v_max_f32_e32 v107, 0, v107
	v_max_f32_e32 v108, 0, v108
	v_max_f32_e32 v109, 0, v109
	v_pk_mul_f32 v[106:107], v[106:107], v[106:107]
	v_pk_mul_f32 v[108:109], v[108:109], v[108:109]
	v_cvt_pk_bf16_f32 v174, v110, v111
	v_cvt_pk_bf16_f32 v175, v112, v113
	v_cvt_pk_bf16_f32 v176, v106, v107
	v_cvt_pk_bf16_f32 v177, v108, v109
	ds_write_b128 v186, v[174:177]
	s_waitcnt lgkmcnt(0)
	s_barrier
	ds_read_b128 v[178:181], v187
	s_waitcnt lgkmcnt(0)
	global_store_dwordx4 v[190:191], v[178:181], off
	v_pk_add_f32 v[102:103], v[102:103], v[118:119]
	v_pk_add_f32 v[104:105], v[104:105], v[120:121]
	v_max_f32_e32 v102, 0, v102
	v_max_f32_e32 v103, 0, v103
	v_max_f32_e32 v104, 0, v104
	v_max_f32_e32 v105, 0, v105
	v_pk_mul_f32 v[102:103], v[102:103], v[102:103]
	v_pk_mul_f32 v[104:105], v[104:105], v[104:105]
	v_pk_add_f32 v[98:99], v[98:99], v[114:115]
	v_pk_add_f32 v[100:101], v[100:101], v[116:117]
	v_max_f32_e32 v98, 0, v98
	v_max_f32_e32 v99, 0, v99
	v_max_f32_e32 v100, 0, v100
	v_max_f32_e32 v101, 0, v101
	v_pk_mul_f32 v[98:99], v[98:99], v[98:99]
	v_pk_mul_f32 v[100:101], v[100:101], v[100:101]
	v_cvt_pk_bf16_f32 v174, v102, v103
	v_cvt_pk_bf16_f32 v175, v104, v105
	v_cvt_pk_bf16_f32 v176, v98, v99
	v_cvt_pk_bf16_f32 v177, v100, v101
	ds_write_b128 v186, v[174:177] offset:8704
	s_waitcnt lgkmcnt(0)
	s_barrier
; __device__ __forceinline__ unsigned pk2(float lo, float hi) { const v2f_t f = {lo, hi}; const v2bf_t b = __builtin_convertvector(f, v2bf_t); return __builtin_bit_cast(unsigned, b); }
;     __device__ __forceinline__ void operator()(const f32x4 (&acc)[2][2][4][2], const Unit& u, int wr, int wc, int fr, int fq) const {
;     ...
;         for (int ai = 0; ai < 2; ++ai)
; #pragma unroll
;             for (int m = 0; m < 4; ++m) { bf16_t* rowp = a1 + (size_t)(row0 + ai * 128 + m * 16) * DFF + col0;
; #pragma unroll
;                 for (int bj = 0; bj < 2; ++bj) { f32x4 v0 = acc[ai][bj][m][0] + bv[bj][0], v1 = acc[ai][bj][m][1] + bv[bj][1];
; #pragma unroll
;                     for (int j = 0; j < 4; ++j) { const float a = fmaxf(v0[j], 0.f), b = fmaxf(v1[j], 0.f); v0[j] = a * a; v1[j] = b * b; }
;                     u32x4 w; w.x = pk2(v0[0], v0[1]); w.y = pk2(v0[2], v0[3]); w.z = pk2(v1[0], v1[1]); w.w = pk2(v1[2], v1[3]);
;                     *(u32x4*)(rowp + bj * 128) = w; } }
	ds_read_b128 v[182:185], v187 offset:8704
	s_waitcnt lgkmcnt(0)
	global_store_dwordx4 v[190:191], v[182:185], off offset:256
	s_mov_b32 s98, 0x80000
	v_lshl_add_u64 v[190:191], v[188:189], 0, s[98:99]
	v_pk_add_f32 v[94:95], v[94:95], v[126:127]
	v_pk_add_f32 v[96:97], v[96:97], v[128:129]
	v_max_f32_e32 v94, 0, v94
	v_max_f32_e32 v95, 0, v95
	v_max_f32_e32 v96, 0, v96
	v_max_f32_e32 v97, 0, v97
	v_pk_mul_f32 v[94:95], v[94:95], v[94:95]
	v_pk_mul_f32 v[96:97], v[96:97], v[96:97]
	v_pk_add_f32 v[90:91], v[90:91], v[122:123]
	v_pk_add_f32 v[92:93], v[92:93], v[124:125]
	v_max_f32_e32 v90, 0, v90
	v_max_f32_e32 v91, 0, v91
	v_max_f32_e32 v92, 0, v92
	v_max_f32_e32 v93, 0, v93
	v_pk_mul_f32 v[90:91], v[90:91], v[90:91]
	v_pk_mul_f32 v[92:93], v[92:93], v[92:93]
	v_cvt_pk_bf16_f32 v174, v94, v95
	v_cvt_pk_bf16_f32 v175, v96, v97
	v_cvt_pk_bf16_f32 v176, v90, v91
	v_cvt_pk_bf16_f32 v177, v92, v93
	ds_write_b128 v186, v[174:177]
	s_waitcnt lgkmcnt(0)
	s_barrier
	ds_read_b128 v[178:181], v187
	s_waitcnt lgkmcnt(0)
	global_store_dwordx4 v[190:191], v[178:181], off
	v_pk_add_f32 v[86:87], v[86:87], v[118:119]
	v_pk_add_f32 v[88:89], v[88:89], v[120:121]
	v_max_f32_e32 v86, 0, v86
	v_max_f32_e32 v87, 0, v87
	v_max_f32_e32 v88, 0, v88
	v_max_f32_e32 v89, 0, v89
	v_pk_mul_f32 v[86:87], v[86:87], v[86:87]
	v_pk_mul_f32 v[88:89], v[88:89], v[88:89]
	v_pk_add_f32 v[82:83], v[82:83], v[114:115]
	v_pk_add_f32 v[84:85], v[84:85], v[116:117]
	v_max_f32_e32 v82, 0, v82
	v_max_f32_e32 v83, 0, v83
	v_max_f32_e32 v84, 0, v84
	v_max_f32_e32 v85, 0, v85
	v_pk_mul_f32 v[82:83], v[82:83], v[82:83]
	v_pk_mul_f32 v[84:85], v[84:85], v[84:85]
	v_cvt_pk_bf16_f32 v174, v86, v87
	v_cvt_pk_bf16_f32 v175, v88, v89
	v_cvt_pk_bf16_f32 v176, v82, v83
	v_cvt_pk_bf16_f32 v177, v84, v85
	ds_write_b128 v186, v[174:177] offset:8704
	s_waitcnt lgkmcnt(0)
	s_barrier
	ds_read_b128 v[182:185], v187 offset:8704
	s_waitcnt lgkmcnt(0)
	global_store_dwordx4 v[190:191], v[182:185], off offset:256
	s_mov_b32 s98, 0xc0000
	v_lshl_add_u64 v[190:191], v[188:189], 0, s[98:99]
	v_pk_add_f32 v[78:79], v[78:79], v[126:127]
	v_pk_add_f32 v[80:81], v[80:81], v[128:129]
	v_max_f32_e32 v78, 0, v78
	v_max_f32_e32 v79, 0, v79
	v_max_f32_e32 v80, 0, v80
	v_max_f32_e32 v81, 0, v81
	v_pk_mul_f32 v[78:79], v[78:79], v[78:79]
	v_pk_mul_f32 v[80:81], v[80:81], v[80:81]
	v_pk_add_f32 v[74:75], v[74:75], v[122:123]
	v_pk_add_f32 v[76:77], v[76:77], v[124:125]
	v_max_f32_e32 v74, 0, v74
	v_max_f32_e32 v75, 0, v75
	v_max_f32_e32 v76, 0, v76
	v_max_f32_e32 v77, 0, v77
	v_pk_mul_f32 v[74:75], v[74:75], v[74:75]
	v_pk_mul_f32 v[76:77], v[76:77], v[76:77]
	v_cvt_pk_bf16_f32 v174, v78, v79
	v_cvt_pk_bf16_f32 v175, v80, v81
	v_cvt_pk_bf16_f32 v176, v74, v75
	v_cvt_pk_bf16_f32 v177, v76, v77
	ds_write_b128 v186, v[174:177]
	s_waitcnt lgkmcnt(0)
	s_barrier
	ds_read_b128 v[178:181], v187
	s_waitcnt lgkmcnt(0)
	global_store_dwordx4 v[190:191], v[178:181], off
	v_pk_add_f32 v[70:71], v[70:71], v[118:119]
	v_pk_add_f32 v[72:73], v[72:73], v[120:121]
	v_max_f32_e32 v70, 0, v70
	v_max_f32_e32 v71, 0, v71
	v_max_f32_e32 v72, 0, v72
	v_max_f32_e32 v73, 0, v73
	v_pk_mul_f32 v[70:71], v[70:71], v[70:71]
	v_pk_mul_f32 v[72:73], v[72:73], v[72:73]
	v_pk_add_f32 v[66:67], v[66:67], v[114:115]
	v_pk_add_f32 v[68:69], v[68:69], v[116:117]
	v_max_f32_e32 v66, 0, v66
	v_max_f32_e32 v67, 0, v67
	v_max_f32_e32 v68, 0, v68
	v_max_f32_e32 v69, 0, v69
	v_pk_mul_f32 v[66:67], v[66:67], v[66:67]
	v_pk_mul_f32 v[68:69], v[68:69], v[68:69]
	v_cvt_pk_bf16_f32 v174, v70, v71
	v_cvt_pk_bf16_f32 v175, v72, v73
	v_cvt_pk_bf16_f32 v176, v66, v67
	v_cvt_pk_bf16_f32 v177, v68, v69
	ds_write_b128 v186, v[174:177] offset:8704
	s_waitcnt lgkmcnt(0)
	s_barrier
	ds_read_b128 v[182:185], v187 offset:8704
	s_waitcnt lgkmcnt(0)
	global_store_dwordx4 v[190:191], v[182:185], off offset:256
	s_mov_b32 s98, 0x200000
	v_lshl_add_u64 v[190:191], v[188:189], 0, s[98:99]
	v_pk_add_f32 v[60:61], v[60:61], v[126:127]
	v_pk_add_f32 v[62:63], v[62:63], v[128:129]
	v_max_f32_e32 v60, 0, v60
	v_max_f32_e32 v61, 0, v61
	v_max_f32_e32 v62, 0, v62
	v_max_f32_e32 v63, 0, v63
	v_pk_mul_f32 v[60:61], v[60:61], v[60:61]
	v_pk_mul_f32 v[62:63], v[62:63], v[62:63]
	v_pk_add_f32 v[56:57], v[56:57], v[122:123]
	v_pk_add_f32 v[58:59], v[58:59], v[124:125]
	v_max_f32_e32 v56, 0, v56
	v_max_f32_e32 v57, 0, v57
	v_max_f32_e32 v58, 0, v58
	v_max_f32_e32 v59, 0, v59
	v_pk_mul_f32 v[56:57], v[56:57], v[56:57]
	v_pk_mul_f32 v[58:59], v[58:59], v[58:59]
	v_cvt_pk_bf16_f32 v174, v60, v61
	v_cvt_pk_bf16_f32 v175, v62, v63
	v_cvt_pk_bf16_f32 v176, v56, v57
	v_cvt_pk_bf16_f32 v177, v58, v59
	ds_write_b128 v186, v[174:177]
	s_waitcnt lgkmcnt(0)
	s_barrier
	ds_read_b128 v[178:181], v187
	s_waitcnt lgkmcnt(0)
	global_store_dwordx4 v[190:191], v[178:181], off
	v_pk_add_f32 v[52:53], v[52:53], v[118:119]
	v_pk_add_f32 v[54:55], v[54:55], v[120:121]
	v_max_f32_e32 v52, 0, v52
	v_max_f32_e32 v53, 0, v53
	v_max_f32_e32 v54, 0, v54
	v_max_f32_e32 v55, 0, v55
	v_pk_mul_f32 v[52:53], v[52:53], v[52:53]
	v_pk_mul_f32 v[54:55], v[54:55], v[54:55]
	v_pk_add_f32 v[48:49], v[48:49], v[114:115]
	v_pk_add_f32 v[50:51], v[50:51], v[116:117]
	v_max_f32_e32 v48, 0, v48
	v_max_f32_e32 v49, 0, v49
	v_max_f32_e32 v50, 0, v50
	v_max_f32_e32 v51, 0, v51
	v_pk_mul_f32 v[48:49], v[48:49], v[48:49]
	v_pk_mul_f32 v[50:51], v[50:51], v[50:51]
	v_cvt_pk_bf16_f32 v174, v52, v53
	v_cvt_pk_bf16_f32 v175, v54, v55
	v_cvt_pk_bf16_f32 v176, v48, v49
	v_cvt_pk_bf16_f32 v177, v50, v51
	ds_write_b128 v186, v[174:177] offset:8704
	s_waitcnt lgkmcnt(0)
	s_barrier
; __device__ __forceinline__ unsigned pk2(float lo, float hi) { const v2f_t f = {lo, hi}; const v2bf_t b = __builtin_convertvector(f, v2bf_t); return __builtin_bit_cast(unsigned, b); }
;     __device__ __forceinline__ void operator()(const f32x4 (&acc)[2][2][4][2], const Unit& u, int wr, int wc, int fr, int fq) const {
;     ...
;         for (int ai = 0; ai < 2; ++ai)
; #pragma unroll
;             for (int m = 0; m < 4; ++m) { bf16_t* rowp = a1 + (size_t)(row0 + ai * 128 + m * 16) * DFF + col0;
; #pragma unroll
;                 for (int bj = 0; bj < 2; ++bj) { f32x4 v0 = acc[ai][bj][m][0] + bv[bj][0], v1 = acc[ai][bj][m][1] + bv[bj][1];
; #pragma unroll
;                     for (int j = 0; j < 4; ++j) { const float a = fmaxf(v0[j], 0.f), b = fmaxf(v1[j], 0.f); v0[j] = a * a; v1[j] = b * b; }
;                     u32x4 w; w.x = pk2(v0[0], v0[1]); w.y = pk2(v0[2], v0[3]); w.z = pk2(v1[0], v1[1]); w.w = pk2(v1[2], v1[3]);
;                     *(u32x4*)(rowp + bj * 128) = w; } }
	ds_read_b128 v[182:185], v187 offset:8704
	s_waitcnt lgkmcnt(0)
	global_store_dwordx4 v[190:191], v[182:185], off offset:256
	s_mov_b32 s98, 0x240000
	v_lshl_add_u64 v[190:191], v[188:189], 0, s[98:99]
	v_pk_add_f32 v[44:45], v[44:45], v[126:127]
	v_pk_add_f32 v[46:47], v[46:47], v[128:129]
	v_max_f32_e32 v44, 0, v44
	v_max_f32_e32 v45, 0, v45
	v_max_f32_e32 v46, 0, v46
	v_max_f32_e32 v47, 0, v47
	v_pk_mul_f32 v[44:45], v[44:45], v[44:45]
	v_pk_mul_f32 v[46:47], v[46:47], v[46:47]
	v_pk_add_f32 v[40:41], v[40:41], v[122:123]
	v_pk_add_f32 v[42:43], v[42:43], v[124:125]
	v_max_f32_e32 v40, 0, v40
	v_max_f32_e32 v41, 0, v41
	v_max_f32_e32 v42, 0, v42
	v_max_f32_e32 v43, 0, v43
	v_pk_mul_f32 v[40:41], v[40:41], v[40:41]
	v_pk_mul_f32 v[42:43], v[42:43], v[42:43]
	v_cvt_pk_bf16_f32 v174, v44, v45
	v_cvt_pk_bf16_f32 v175, v46, v47
	v_cvt_pk_bf16_f32 v176, v40, v41
	v_cvt_pk_bf16_f32 v177, v42, v43
	ds_write_b128 v186, v[174:177]
	s_waitcnt lgkmcnt(0)
	s_barrier
	ds_read_b128 v[178:181], v187
	s_waitcnt lgkmcnt(0)
	global_store_dwordx4 v[190:191], v[178:181], off
	v_pk_add_f32 v[36:37], v[36:37], v[118:119]
	v_pk_add_f32 v[38:39], v[38:39], v[120:121]
	v_max_f32_e32 v36, 0, v36
	v_max_f32_e32 v37, 0, v37
	v_max_f32_e32 v38, 0, v38
	v_max_f32_e32 v39, 0, v39
	v_pk_mul_f32 v[36:37], v[36:37], v[36:37]
	v_pk_mul_f32 v[38:39], v[38:39], v[38:39]
	v_pk_add_f32 v[32:33], v[32:33], v[114:115]
	v_pk_add_f32 v[34:35], v[34:35], v[116:117]
	v_max_f32_e32 v32, 0, v32
	v_max_f32_e32 v33, 0, v33
	v_max_f32_e32 v34, 0, v34
	v_max_f32_e32 v35, 0, v35
	v_pk_mul_f32 v[32:33], v[32:33], v[32:33]
	v_pk_mul_f32 v[34:35], v[34:35], v[34:35]
	v_cvt_pk_bf16_f32 v174, v36, v37
	v_cvt_pk_bf16_f32 v175, v38, v39
	v_cvt_pk_bf16_f32 v176, v32, v33
	v_cvt_pk_bf16_f32 v177, v34, v35
	ds_write_b128 v186, v[174:177] offset:8704
	s_waitcnt lgkmcnt(0)
	s_barrier
	ds_read_b128 v[182:185], v187 offset:8704
	s_waitcnt lgkmcnt(0)
	global_store_dwordx4 v[190:191], v[182:185], off offset:256
	s_mov_b32 s98, 0x280000
	v_lshl_add_u64 v[190:191], v[188:189], 0, s[98:99]
	v_pk_add_f32 v[28:29], v[28:29], v[126:127]
	v_pk_add_f32 v[30:31], v[30:31], v[128:129]
	v_max_f32_e32 v28, 0, v28
	v_max_f32_e32 v29, 0, v29
	v_max_f32_e32 v30, 0, v30
	v_max_f32_e32 v31, 0, v31
	v_pk_mul_f32 v[28:29], v[28:29], v[28:29]
	v_pk_mul_f32 v[30:31], v[30:31], v[30:31]
	v_pk_add_f32 v[24:25], v[24:25], v[122:123]
	v_pk_add_f32 v[26:27], v[26:27], v[124:125]
	v_max_f32_e32 v24, 0, v24
	v_max_f32_e32 v25, 0, v25
	v_max_f32_e32 v26, 0, v26
	v_max_f32_e32 v27, 0, v27
	v_pk_mul_f32 v[24:25], v[24:25], v[24:25]
	v_pk_mul_f32 v[26:27], v[26:27], v[26:27]
	v_cvt_pk_bf16_f32 v174, v28, v29
	v_cvt_pk_bf16_f32 v175, v30, v31
	v_cvt_pk_bf16_f32 v176, v24, v25
	v_cvt_pk_bf16_f32 v177, v26, v27
	ds_write_b128 v186, v[174:177]
	s_waitcnt lgkmcnt(0)
	s_barrier
	ds_read_b128 v[178:181], v187
	s_waitcnt lgkmcnt(0)
	global_store_dwordx4 v[190:191], v[178:181], off
	v_pk_add_f32 v[20:21], v[20:21], v[118:119]
	v_pk_add_f32 v[22:23], v[22:23], v[120:121]
	v_max_f32_e32 v20, 0, v20
	v_max_f32_e32 v21, 0, v21
	v_max_f32_e32 v22, 0, v22
	v_max_f32_e32 v23, 0, v23
	v_pk_mul_f32 v[20:21], v[20:21], v[20:21]
	v_pk_mul_f32 v[22:23], v[22:23], v[22:23]
	v_pk_add_f32 v[16:17], v[16:17], v[114:115]
	v_pk_add_f32 v[18:19], v[18:19], v[116:117]
	v_max_f32_e32 v16, 0, v16
	v_max_f32_e32 v17, 0, v17
	v_max_f32_e32 v18, 0, v18
	v_max_f32_e32 v19, 0, v19
	v_pk_mul_f32 v[16:17], v[16:17], v[16:17]
	v_pk_mul_f32 v[18:19], v[18:19], v[18:19]
	v_cvt_pk_bf16_f32 v174, v20, v21
	v_cvt_pk_bf16_f32 v175, v22, v23
	v_cvt_pk_bf16_f32 v176, v16, v17
	v_cvt_pk_bf16_f32 v177, v18, v19
	ds_write_b128 v186, v[174:177] offset:8704
	s_waitcnt lgkmcnt(0)
	s_barrier
	ds_read_b128 v[182:185], v187 offset:8704
	s_waitcnt lgkmcnt(0)
	global_store_dwordx4 v[190:191], v[182:185], off offset:256
	s_mov_b32 s98, 0x2c0000
	v_lshl_add_u64 v[190:191], v[188:189], 0, s[98:99]
	v_pk_add_f32 v[12:13], v[12:13], v[126:127]
	v_pk_add_f32 v[14:15], v[14:15], v[128:129]
	v_max_f32_e32 v12, 0, v12
	v_max_f32_e32 v13, 0, v13
	v_max_f32_e32 v14, 0, v14
	v_max_f32_e32 v15, 0, v15
	v_pk_mul_f32 v[12:13], v[12:13], v[12:13]
	v_pk_mul_f32 v[14:15], v[14:15], v[14:15]
	v_pk_add_f32 v[8:9], v[8:9], v[122:123]
	v_pk_add_f32 v[10:11], v[10:11], v[124:125]
	v_max_f32_e32 v8, 0, v8
	v_max_f32_e32 v9, 0, v9
	v_max_f32_e32 v10, 0, v10
	v_max_f32_e32 v11, 0, v11
	v_pk_mul_f32 v[8:9], v[8:9], v[8:9]
	v_pk_mul_f32 v[10:11], v[10:11], v[10:11]
	v_cvt_pk_bf16_f32 v174, v12, v13
	v_cvt_pk_bf16_f32 v175, v14, v15
	v_cvt_pk_bf16_f32 v176, v8, v9
	v_cvt_pk_bf16_f32 v177, v10, v11
	ds_write_b128 v186, v[174:177]
	s_waitcnt lgkmcnt(0)
	s_barrier
	ds_read_b128 v[178:181], v187
	s_waitcnt lgkmcnt(0)
	global_store_dwordx4 v[190:191], v[178:181], off
	v_pk_add_f32 v[4:5], v[4:5], v[118:119]
	v_pk_add_f32 v[6:7], v[6:7], v[120:121]
	v_max_f32_e32 v4, 0, v4
	v_max_f32_e32 v5, 0, v5
	v_max_f32_e32 v6, 0, v6
	v_max_f32_e32 v7, 0, v7
	v_pk_mul_f32 v[4:5], v[4:5], v[4:5]
	v_pk_mul_f32 v[6:7], v[6:7], v[6:7]
	v_pk_add_f32 v[0:1], v[0:1], v[114:115]
	v_pk_add_f32 v[2:3], v[2:3], v[116:117]
	v_max_f32_e32 v0, 0, v0
	v_max_f32_e32 v1, 0, v1
	v_max_f32_e32 v2, 0, v2
	v_max_f32_e32 v3, 0, v3
	v_pk_mul_f32 v[0:1], v[0:1], v[0:1]
	v_pk_mul_f32 v[2:3], v[2:3], v[2:3]
	v_cvt_pk_bf16_f32 v174, v4, v5
	v_cvt_pk_bf16_f32 v175, v6, v7
	v_cvt_pk_bf16_f32 v176, v0, v1
	v_cvt_pk_bf16_f32 v177, v2, v3
	ds_write_b128 v186, v[174:177] offset:8704
	s_waitcnt lgkmcnt(0)
	s_barrier
	ds_read_b128 v[182:185], v187 offset:8704
	s_waitcnt lgkmcnt(0)
	global_store_dwordx4 v[190:191], v[182:185], off offset:256
	s_and_b64 vcc, exec, s[26:27]
	s_mov_b64 s[36:37], s[24:25]
	s_cbranch_vccnz .LBB0_861
